# write-through-sc1-stores-for-streaming-EpiMul-and-SwiGLU-outputs
# speedup vs baseline: 1.0511x; 1.0031x over previous
.LBB0_380:
	s_lshl_b32 s5, s5, 8
	s_lshl_b32 s6, s6, 7
	s_add_i32 s5, s5, s6
	v_add_u32_e32 v130, s5, v222
	v_ashrrev_i32_e32 v131, 31, v130
	v_lshlrev_b64 v[132:133], 6, v[130:131]
	v_lshl_add_u64 v[132:133], v[204:205], 0, v[132:133]
	global_load_dwordx4 v[136:139], v[132:133], off
	global_load_dwordx4 v[140:143], v[132:133], off offset:1024
	global_load_dwordx4 v[144:147], v[132:133], off offset:2048
	global_load_dwordx4 v[148:151], v[132:133], off offset:3072
	v_add_u32_e32 v168, 0x80, v130
	v_ashrrev_i32_e32 v169, 31, v168
	v_lshlrev_b64 v[168:169], 6, v[168:169]
	v_lshl_add_u64 v[168:169], v[204:205], 0, v[168:169]
	global_load_dwordx4 v[152:155], v[168:169], off
	global_load_dwordx4 v[156:159], v[168:169], off offset:1024
	global_load_dwordx4 v[160:163], v[168:169], off offset:2048
	global_load_dwordx4 v[164:167], v[168:169], off offset:3072
	s_lshl_b32 s4, s4, 7
	s_ashr_i32 s5, s4, 31
	s_lshl_b64 s[38:39], s[4:5], 1
	s_waitcnt vmcnt(7)
	v_add_f32_e32 v131, v136, v137
	v_add_f32_e32 v132, v138, v139
	v_add_f32_e32 v131, v131, v132
	v_mov_b32_e32 v132, v131
	s_nop 1
	v_permlane16_swap_b32_e32 v131, v132
	v_add_f32_e32 v131, v131, v132
	v_mov_b32_e32 v132, v131
	s_nop 1
	v_permlane32_swap_b32_e32 v131, v132
	v_add_f32_e32 v131, v131, v132
	v_fmamk_f32 v131, v131, 0x3a800000, v225
	v_cmp_gt_f32_e32 vcc, s3, v131
	v_mul_f32_e32 v132, 0x4b800000, v131
	s_nop 0
	v_cndmask_b32_e32 v131, v131, v132, vcc
	v_rsq_f32_e32 v131, v131
	s_nop 0
	v_mul_f32_e32 v132, 0x45800000, v131
	v_cndmask_b32_e32 v132, v131, v132, vcc
	v_pk_mul_f32 v[126:127], v[126:127], v[132:133] op_sel_hi:[1,0]
	v_pk_mul_f32 v[122:123], v[122:123], v[132:133] op_sel_hi:[1,0]
	v_mul_f32_e32 v131, 0xbfb8aa3b, v126
	v_exp_f32_e32 v131, v131
	v_pk_mul_f32 v[124:125], v[124:125], v[132:133] op_sel_hi:[1,0]
	v_pk_mul_f32 v[118:119], v[118:119], v[132:133] op_sel_hi:[1,0]
	v_pk_mul_f32 v[114:115], v[114:115], v[132:133] op_sel_hi:[1,0]
	v_add_f32_e32 v131, 1.0, v131
	v_rcp_f32_e32 v134, v131
	v_mul_f32_e32 v131, 0xbfb8aa3b, v127
	v_exp_f32_e32 v131, v131
	v_pk_mul_f32 v[116:117], v[116:117], v[132:133] op_sel_hi:[1,0]
	v_add_f32_e32 v131, 1.0, v131
	v_rcp_f32_e32 v135, v131
	s_nop 0
	v_pk_mul_f32 v[126:127], v[126:127], v[134:135]
	s_nop 0
	v_pk_mul_f32 v[122:123], v[122:123], v[126:127]
	v_pk_mul_f32 v[126:127], v[128:129], v[132:133] op_sel_hi:[1,0]
	s_nop 0
	v_mul_f32_e32 v128, 0xbfb8aa3b, v126
	v_mul_f32_e32 v129, 0xbfb8aa3b, v127
	v_exp_f32_e32 v128, v128
	v_exp_f32_e32 v129, v129
	v_add_f32_e32 v128, 1.0, v128
	v_add_f32_e32 v129, 1.0, v129
	v_rcp_f32_e32 v128, v128
	v_rcp_f32_e32 v129, v129
	s_nop 0
	v_pk_mul_f32 v[126:127], v[126:127], v[128:129]
	s_nop 0
	v_pk_mul_f32 v[124:125], v[124:125], v[126:127]
	v_mul_f32_e32 v126, 0xbfb8aa3b, v118
	v_mul_f32_e32 v127, 0xbfb8aa3b, v119
	v_exp_f32_e32 v126, v126
	v_exp_f32_e32 v127, v127
	v_add_f32_e32 v126, 1.0, v126
	v_add_f32_e32 v127, 1.0, v127
	v_rcp_f32_e32 v126, v126
	v_rcp_f32_e32 v127, v127
	s_nop 0
	v_pk_mul_f32 v[118:119], v[118:119], v[126:127]
	s_nop 0
	v_pk_mul_f32 v[118:119], v[114:115], v[118:119]
	v_pk_mul_f32 v[114:115], v[120:121], v[132:133] op_sel_hi:[1,0]
	s_nop 0
	v_mul_f32_e32 v120, 0xbfb8aa3b, v114
	v_mul_f32_e32 v121, 0xbfb8aa3b, v115
	v_exp_f32_e32 v120, v120
	v_exp_f32_e32 v121, v121
	v_add_f32_e32 v120, 1.0, v120
	v_add_f32_e32 v121, 1.0, v121
	v_rcp_f32_e32 v120, v120
	v_rcp_f32_e32 v121, v121
	s_nop 0
	v_pk_mul_f32 v[114:115], v[114:115], v[120:121]
	s_nop 0
	v_pk_mul_f32 v[120:121], v[116:117], v[114:115]
	v_cvt_pk_bf16_f32 v116, v118, v119
	v_mov_b64_e32 v[118:119], s[62:63]
	v_cvt_pk_bf16_f32 v117, v120, v121
	v_mad_i64_i32 v[120:121], s[6:7], v130, s16, v[118:119]
	v_lshl_add_u64 v[120:121], v[120:121], 0, s[38:39]
	v_lshl_add_u64 v[120:121], v[120:121], 0, s[68:69]
	v_cvt_pk_bf16_f32 v114, v122, v123
	v_cvt_pk_bf16_f32 v115, v124, v125
	v_lshl_add_u64 v[120:121], v[120:121], 0, v[96:97]
	global_store_dwordx4 v[120:121], v[114:117], off sc1
	s_nop 1
	v_or_b32_e32 v114, 16, v130
	v_ashrrev_i32_e32 v115, 31, v114
	v_lshlrev_b64 v[116:117], 6, v[114:115]
	v_lshl_add_u64 v[116:117], v[204:205], 0, v[116:117]
	s_waitcnt vmcnt(7)
	v_add_f32_e32 v115, v140, v141
	v_add_f32_e32 v116, v142, v143
	v_add_f32_e32 v115, v115, v116
	v_mov_b32_e32 v116, v115
	s_nop 1
	v_permlane16_swap_b32_e32 v115, v116
	v_add_f32_e32 v115, v115, v116
	v_mov_b32_e32 v116, v115
	s_nop 1
	v_permlane32_swap_b32_e32 v115, v116
	v_add_f32_e32 v115, v115, v116
	v_fmamk_f32 v115, v115, 0x3a800000, v225
	v_cmp_gt_f32_e32 vcc, s3, v115
	v_mul_f32_e32 v116, 0x4b800000, v115
	s_nop 0
	v_cndmask_b32_e32 v115, v115, v116, vcc
	v_rsq_f32_e32 v115, v115
	s_nop 0
	v_mul_f32_e32 v116, 0x45800000, v115
	v_cndmask_b32_e32 v116, v115, v116, vcc
	v_pk_mul_f32 v[110:111], v[110:111], v[116:117] op_sel_hi:[1,0]
	v_pk_mul_f32 v[106:107], v[106:107], v[116:117] op_sel_hi:[1,0]
	v_mul_f32_e32 v115, 0xbfb8aa3b, v110
	v_exp_f32_e32 v115, v115
	v_pk_mul_f32 v[108:109], v[108:109], v[116:117] op_sel_hi:[1,0]
	v_pk_mul_f32 v[102:103], v[102:103], v[116:117] op_sel_hi:[1,0]
	v_pk_mul_f32 v[98:99], v[98:99], v[116:117] op_sel_hi:[1,0]
	v_add_f32_e32 v115, 1.0, v115
	v_rcp_f32_e32 v120, v115
	v_mul_f32_e32 v115, 0xbfb8aa3b, v111
	v_exp_f32_e32 v115, v115
	v_pk_mul_f32 v[100:101], v[100:101], v[116:117] op_sel_hi:[1,0]
	v_add_f32_e32 v115, 1.0, v115
	v_rcp_f32_e32 v121, v115
	s_nop 0
	v_pk_mul_f32 v[110:111], v[110:111], v[120:121]
	s_nop 0
	v_pk_mul_f32 v[106:107], v[106:107], v[110:111]
	v_pk_mul_f32 v[110:111], v[112:113], v[116:117] op_sel_hi:[1,0]
	s_nop 0
	v_mul_f32_e32 v112, 0xbfb8aa3b, v110
	v_mul_f32_e32 v113, 0xbfb8aa3b, v111
	v_exp_f32_e32 v112, v112
	v_exp_f32_e32 v113, v113
	v_add_f32_e32 v112, 1.0, v112
	v_add_f32_e32 v113, 1.0, v113
	v_rcp_f32_e32 v112, v112
	v_rcp_f32_e32 v113, v113
	s_nop 0
	v_pk_mul_f32 v[110:111], v[110:111], v[112:113]
	s_nop 0
	v_pk_mul_f32 v[108:109], v[108:109], v[110:111]
	v_mul_f32_e32 v110, 0xbfb8aa3b, v102
	v_mul_f32_e32 v111, 0xbfb8aa3b, v103
	v_exp_f32_e32 v110, v110
	v_exp_f32_e32 v111, v111
	v_add_f32_e32 v110, 1.0, v110
	v_add_f32_e32 v111, 1.0, v111
	v_rcp_f32_e32 v110, v110
	v_rcp_f32_e32 v111, v111
	s_nop 0
	v_pk_mul_f32 v[102:103], v[102:103], v[110:111]
	s_nop 0
	v_pk_mul_f32 v[102:103], v[98:99], v[102:103]
	v_pk_mul_f32 v[98:99], v[104:105], v[116:117] op_sel_hi:[1,0]
	s_nop 0
	v_mul_f32_e32 v104, 0xbfb8aa3b, v98
	v_mul_f32_e32 v105, 0xbfb8aa3b, v99
	v_exp_f32_e32 v104, v104
	v_exp_f32_e32 v105, v105
	v_add_f32_e32 v104, 1.0, v104
	v_add_f32_e32 v105, 1.0, v105
	v_rcp_f32_e32 v104, v104
	v_rcp_f32_e32 v105, v105
	s_nop 0
	v_pk_mul_f32 v[98:99], v[98:99], v[104:105]
	s_nop 0
	v_pk_mul_f32 v[104:105], v[100:101], v[98:99]
	v_cvt_pk_bf16_f32 v100, v102, v103
	v_mad_i64_i32 v[102:103], s[4:5], v114, s16, v[118:119]
	v_lshl_add_u64 v[102:103], v[102:103], 0, s[38:39]
	v_lshl_add_u64 v[102:103], v[102:103], 0, s[68:69]
	v_cvt_pk_bf16_f32 v98, v106, v107
	v_cvt_pk_bf16_f32 v99, v108, v109
	v_cvt_pk_bf16_f32 v101, v104, v105
	v_lshl_add_u64 v[102:103], v[102:103], 0, v[96:97]
	global_store_dwordx4 v[102:103], v[98:101], off sc1
	s_nop 1
	v_or_b32_e32 v98, 32, v130
	v_ashrrev_i32_e32 v99, 31, v98
	v_lshlrev_b64 v[100:101], 6, v[98:99]
	v_lshl_add_u64 v[100:101], v[204:205], 0, v[100:101]
	s_waitcnt vmcnt(7)
	v_add_f32_e32 v99, v144, v145
	v_add_f32_e32 v100, v146, v147
	v_add_f32_e32 v99, v99, v100
	v_mov_b32_e32 v100, v99
	s_nop 1
	v_permlane16_swap_b32_e32 v99, v100
	v_add_f32_e32 v99, v99, v100
	v_mov_b32_e32 v100, v99
	s_nop 1
	v_permlane32_swap_b32_e32 v99, v100
	v_add_f32_e32 v99, v99, v100
	v_fmamk_f32 v99, v99, 0x3a800000, v225
	v_cmp_gt_f32_e32 vcc, s3, v99
	v_mul_f32_e32 v100, 0x4b800000, v99
	s_nop 0
	v_cndmask_b32_e32 v99, v99, v100, vcc
	v_rsq_f32_e32 v99, v99
	s_nop 0
	v_mul_f32_e32 v100, 0x45800000, v99
	v_cndmask_b32_e32 v100, v99, v100, vcc
	v_pk_mul_f32 v[92:93], v[92:93], v[100:101] op_sel_hi:[1,0]
	v_pk_mul_f32 v[88:89], v[88:89], v[100:101] op_sel_hi:[1,0]
	v_mul_f32_e32 v99, 0xbfb8aa3b, v92
	v_exp_f32_e32 v99, v99
	v_pk_mul_f32 v[90:91], v[90:91], v[100:101] op_sel_hi:[1,0]
	v_pk_mul_f32 v[84:85], v[84:85], v[100:101] op_sel_hi:[1,0]
	v_pk_mul_f32 v[80:81], v[80:81], v[100:101] op_sel_hi:[1,0]
	v_add_f32_e32 v99, 1.0, v99
	v_rcp_f32_e32 v102, v99
	v_mul_f32_e32 v99, 0xbfb8aa3b, v93
	v_exp_f32_e32 v99, v99
	v_pk_mul_f32 v[82:83], v[82:83], v[100:101] op_sel_hi:[1,0]
	v_add_f32_e32 v99, 1.0, v99
	v_rcp_f32_e32 v103, v99
	s_nop 0
	v_pk_mul_f32 v[92:93], v[92:93], v[102:103]
	s_nop 0
	v_pk_mul_f32 v[88:89], v[88:89], v[92:93]
	v_pk_mul_f32 v[92:93], v[94:95], v[100:101] op_sel_hi:[1,0]
	s_nop 0
	v_mul_f32_e32 v94, 0xbfb8aa3b, v92
	v_mul_f32_e32 v95, 0xbfb8aa3b, v93
	v_exp_f32_e32 v94, v94
	v_exp_f32_e32 v95, v95
	v_add_f32_e32 v94, 1.0, v94
	v_add_f32_e32 v95, 1.0, v95
	v_rcp_f32_e32 v94, v94
	v_rcp_f32_e32 v95, v95
	s_nop 0
	v_pk_mul_f32 v[92:93], v[92:93], v[94:95]
	s_nop 0
	v_pk_mul_f32 v[90:91], v[90:91], v[92:93]
	v_mul_f32_e32 v92, 0xbfb8aa3b, v84
	v_mul_f32_e32 v93, 0xbfb8aa3b, v85
	v_exp_f32_e32 v92, v92
	v_exp_f32_e32 v93, v93
	v_add_f32_e32 v92, 1.0, v92
	v_add_f32_e32 v93, 1.0, v93
	v_rcp_f32_e32 v92, v92
	v_rcp_f32_e32 v93, v93
	s_nop 0
	v_pk_mul_f32 v[84:85], v[84:85], v[92:93]
	s_nop 0
	v_pk_mul_f32 v[84:85], v[80:81], v[84:85]
	v_pk_mul_f32 v[80:81], v[86:87], v[100:101] op_sel_hi:[1,0]
	s_nop 0
	v_mul_f32_e32 v86, 0xbfb8aa3b, v80
	v_mul_f32_e32 v87, 0xbfb8aa3b, v81
	v_exp_f32_e32 v86, v86
	v_exp_f32_e32 v87, v87
	v_add_f32_e32 v86, 1.0, v86
	v_add_f32_e32 v87, 1.0, v87
	v_rcp_f32_e32 v86, v86
	v_rcp_f32_e32 v87, v87
	s_nop 0
	v_pk_mul_f32 v[80:81], v[80:81], v[86:87]
	s_nop 0
	v_pk_mul_f32 v[86:87], v[82:83], v[80:81]
	v_cvt_pk_bf16_f32 v82, v84, v85
	v_mad_i64_i32 v[84:85], s[4:5], v98, s16, v[118:119]
	v_lshl_add_u64 v[84:85], v[84:85], 0, s[38:39]
	v_lshl_add_u64 v[84:85], v[84:85], 0, s[68:69]
	v_cvt_pk_bf16_f32 v80, v88, v89
	v_cvt_pk_bf16_f32 v81, v90, v91
	v_cvt_pk_bf16_f32 v83, v86, v87
	v_lshl_add_u64 v[84:85], v[84:85], 0, v[96:97]
	global_store_dwordx4 v[84:85], v[80:83], off sc1
	s_nop 1
	v_or_b32_e32 v80, 48, v130
	v_ashrrev_i32_e32 v81, 31, v80
	v_lshlrev_b64 v[82:83], 6, v[80:81]
	v_lshl_add_u64 v[82:83], v[204:205], 0, v[82:83]
	s_waitcnt vmcnt(7)
	v_add_f32_e32 v81, v148, v149
	v_add_f32_e32 v82, v150, v151
	v_add_f32_e32 v81, v81, v82
	v_mov_b32_e32 v82, v81
	s_nop 1
	v_permlane16_swap_b32_e32 v81, v82
	v_add_f32_e32 v81, v81, v82
	v_mov_b32_e32 v82, v81
	s_nop 1
	v_permlane32_swap_b32_e32 v81, v82
	v_add_f32_e32 v81, v81, v82
	v_fmamk_f32 v81, v81, 0x3a800000, v225
	v_cmp_gt_f32_e32 vcc, s3, v81
	v_mul_f32_e32 v82, 0x4b800000, v81
	s_nop 0
	v_cndmask_b32_e32 v81, v81, v82, vcc
	v_rsq_f32_e32 v81, v81
	s_nop 0
	v_mul_f32_e32 v82, 0x45800000, v81
	v_cndmask_b32_e32 v82, v81, v82, vcc
	v_pk_mul_f32 v[76:77], v[76:77], v[82:83] op_sel_hi:[1,0]
	v_pk_mul_f32 v[72:73], v[72:73], v[82:83] op_sel_hi:[1,0]
	v_mul_f32_e32 v81, 0xbfb8aa3b, v76
	v_exp_f32_e32 v81, v81
	v_pk_mul_f32 v[74:75], v[74:75], v[82:83] op_sel_hi:[1,0]
	v_pk_mul_f32 v[68:69], v[68:69], v[82:83] op_sel_hi:[1,0]
	v_pk_mul_f32 v[64:65], v[64:65], v[82:83] op_sel_hi:[1,0]
	v_add_f32_e32 v81, 1.0, v81
	v_rcp_f32_e32 v84, v81
	v_mul_f32_e32 v81, 0xbfb8aa3b, v77
	v_exp_f32_e32 v81, v81
	v_pk_mul_f32 v[66:67], v[66:67], v[82:83] op_sel_hi:[1,0]
	v_cmp_ne_u32_e32 vcc, 0, v247
	s_and_b64 vcc, exec, vcc
	v_add_f32_e32 v81, 1.0, v81
	v_rcp_f32_e32 v85, v81
	s_nop 0
	v_pk_mul_f32 v[76:77], v[76:77], v[84:85]
	s_nop 0
	v_pk_mul_f32 v[72:73], v[72:73], v[76:77]
	v_pk_mul_f32 v[76:77], v[78:79], v[82:83] op_sel_hi:[1,0]
	s_nop 0
	v_mul_f32_e32 v78, 0xbfb8aa3b, v76
	v_mul_f32_e32 v79, 0xbfb8aa3b, v77
	v_exp_f32_e32 v78, v78
	v_exp_f32_e32 v79, v79
	v_add_f32_e32 v78, 1.0, v78
	v_add_f32_e32 v79, 1.0, v79
	v_rcp_f32_e32 v78, v78
	v_rcp_f32_e32 v79, v79
	s_nop 0
	v_pk_mul_f32 v[76:77], v[76:77], v[78:79]
	s_nop 0
	v_pk_mul_f32 v[74:75], v[74:75], v[76:77]
	v_mul_f32_e32 v76, 0xbfb8aa3b, v68
	v_mul_f32_e32 v77, 0xbfb8aa3b, v69
	v_exp_f32_e32 v76, v76
	v_exp_f32_e32 v77, v77
	v_add_f32_e32 v76, 1.0, v76
	v_add_f32_e32 v77, 1.0, v77
	v_rcp_f32_e32 v76, v76
	v_rcp_f32_e32 v77, v77
	s_nop 0
	v_pk_mul_f32 v[68:69], v[68:69], v[76:77]
	s_nop 0
	v_pk_mul_f32 v[68:69], v[64:65], v[68:69]
	v_pk_mul_f32 v[64:65], v[70:71], v[82:83] op_sel_hi:[1,0]
	s_nop 0
	v_mul_f32_e32 v70, 0xbfb8aa3b, v64
	v_mul_f32_e32 v71, 0xbfb8aa3b, v65
	v_exp_f32_e32 v70, v70
	v_exp_f32_e32 v71, v71
	v_add_f32_e32 v70, 1.0, v70
	v_add_f32_e32 v71, 1.0, v71
	v_rcp_f32_e32 v70, v70
	v_rcp_f32_e32 v71, v71
	s_nop 0
	v_pk_mul_f32 v[64:65], v[64:65], v[70:71]
	s_nop 0
	v_pk_mul_f32 v[70:71], v[66:67], v[64:65]
	v_cvt_pk_bf16_f32 v66, v68, v69
	v_mad_i64_i32 v[68:69], s[4:5], v80, s16, v[118:119]
	v_lshl_add_u64 v[68:69], v[68:69], 0, s[38:39]
	v_lshl_add_u64 v[68:69], v[68:69], 0, s[68:69]
	v_cvt_pk_bf16_f32 v64, v72, v73
	v_cvt_pk_bf16_f32 v65, v74, v75
	v_cvt_pk_bf16_f32 v67, v70, v71
	v_lshl_add_u64 v[68:69], v[68:69], 0, v[96:97]
	global_store_dwordx4 v[68:69], v[64:67], off sc1
	s_cbranch_vccz .LBB0_382
	s_waitcnt vmcnt(4)
	s_and_b64 vcc, exec, s[36:37]
	s_mov_b64 s[30:31], -1
	s_cbranch_vccnz .LBB0_349
	s_branch .LBB0_383
.LBB0_382:
	s_nop 0
	v_add_u32_e32 v64, 0x80, v130
	v_ashrrev_i32_e32 v65, 31, v64
	v_lshlrev_b64 v[66:67], 6, v[64:65]
	v_lshl_add_u64 v[66:67], v[204:205], 0, v[66:67]
	s_waitcnt vmcnt(7)
	v_add_f32_e32 v65, v152, v153
	v_add_f32_e32 v66, v154, v155
	v_add_f32_e32 v65, v65, v66
	v_mov_b32_e32 v66, v65
	s_nop 1
	v_permlane16_swap_b32_e32 v65, v66
	v_add_f32_e32 v65, v65, v66
	v_mov_b32_e32 v66, v65
	s_nop 1
	v_permlane32_swap_b32_e32 v65, v66
	v_add_f32_e32 v65, v65, v66
	v_fmamk_f32 v65, v65, 0x3a800000, v225
	v_cmp_gt_f32_e32 vcc, s3, v65
	v_mul_f32_e32 v66, 0x4b800000, v65
	s_nop 0
	v_cndmask_b32_e32 v65, v65, v66, vcc
	v_rsq_f32_e32 v65, v65
	s_nop 0
	v_mul_f32_e32 v66, 0x45800000, v65
	v_cndmask_b32_e32 v66, v65, v66, vcc
	v_pk_mul_f32 v[48:49], v[48:49], v[66:67] op_sel_hi:[1,0]
	v_pk_mul_f32 v[60:61], v[60:61], v[66:67] op_sel_hi:[1,0]
	v_mul_f32_e32 v65, 0xbfb8aa3b, v48
	v_exp_f32_e32 v65, v65
	v_pk_mul_f32 v[50:51], v[50:51], v[66:67] op_sel_hi:[1,0]
	v_pk_mul_f32 v[56:57], v[56:57], v[66:67] op_sel_hi:[1,0]
	v_pk_mul_f32 v[52:53], v[52:53], v[66:67] op_sel_hi:[1,0]
	v_add_f32_e32 v65, 1.0, v65
	v_rcp_f32_e32 v68, v65
	v_mul_f32_e32 v65, 0xbfb8aa3b, v49
	v_exp_f32_e32 v65, v65
	v_pk_mul_f32 v[62:63], v[62:63], v[66:67] op_sel_hi:[1,0]
	v_pk_mul_f32 v[54:55], v[54:55], v[66:67] op_sel_hi:[1,0]
	v_add_f32_e32 v65, 1.0, v65
	v_rcp_f32_e32 v69, v65
	s_nop 0
	v_pk_mul_f32 v[48:49], v[48:49], v[68:69]
	s_nop 0
	v_pk_mul_f32 v[48:49], v[60:61], v[48:49]
	v_mul_f32_e32 v60, 0xbfb8aa3b, v50
	v_mul_f32_e32 v61, 0xbfb8aa3b, v51
	v_exp_f32_e32 v60, v60
	v_exp_f32_e32 v61, v61
	v_cvt_pk_bf16_f32 v48, v48, v49
	v_add_f32_e32 v60, 1.0, v60
	v_add_f32_e32 v61, 1.0, v61
	v_rcp_f32_e32 v60, v60
	v_rcp_f32_e32 v61, v61
	s_nop 0
	v_pk_mul_f32 v[50:51], v[50:51], v[60:61]
	v_mul_f32_e32 v60, 0xbfb8aa3b, v56
	v_mul_f32_e32 v61, 0xbfb8aa3b, v57
	v_exp_f32_e32 v60, v60
	v_exp_f32_e32 v61, v61
	v_pk_mul_f32 v[50:51], v[62:63], v[50:51]
	v_add_f32_e32 v60, 1.0, v60
	v_add_f32_e32 v61, 1.0, v61
	v_rcp_f32_e32 v60, v60
	v_rcp_f32_e32 v61, v61
	v_cvt_pk_bf16_f32 v49, v50, v51
	v_pk_mul_f32 v[56:57], v[56:57], v[60:61]
	s_nop 0
	v_pk_mul_f32 v[52:53], v[52:53], v[56:57]
	v_pk_mul_f32 v[56:57], v[58:59], v[66:67] op_sel_hi:[1,0]
	v_cvt_pk_bf16_f32 v50, v52, v53
	v_mul_f32_e32 v58, 0xbfb8aa3b, v56
	v_mul_f32_e32 v59, 0xbfb8aa3b, v57
	v_exp_f32_e32 v58, v58
	v_exp_f32_e32 v59, v59
	v_mov_b64_e32 v[52:53], s[62:63]
	v_add_f32_e32 v58, 1.0, v58
	v_add_f32_e32 v59, 1.0, v59
	v_rcp_f32_e32 v58, v58
	v_rcp_f32_e32 v59, v59
	s_nop 0
	v_pk_mul_f32 v[56:57], v[56:57], v[58:59]
	s_nop 0
	v_pk_mul_f32 v[54:55], v[54:55], v[56:57]
	s_nop 0
	v_cvt_pk_bf16_f32 v51, v54, v55
	v_mad_i64_i32 v[54:55], s[4:5], v64, s16, v[52:53]
	v_lshl_add_u64 v[54:55], v[54:55], 0, s[38:39]
	v_lshl_add_u64 v[54:55], v[54:55], 0, s[68:69]
	v_lshl_add_u64 v[54:55], v[54:55], 0, v[96:97]
	global_store_dwordx4 v[54:55], v[48:51], off sc1
	s_nop 1
	v_add_u32_e32 v48, 0x90, v130
	v_ashrrev_i32_e32 v49, 31, v48
	v_lshlrev_b64 v[50:51], 6, v[48:49]
	v_lshl_add_u64 v[50:51], v[204:205], 0, v[50:51]
	s_waitcnt vmcnt(7)
	v_add_f32_e32 v49, v156, v157
	v_add_f32_e32 v50, v158, v159
	v_add_f32_e32 v49, v49, v50
	v_mov_b32_e32 v50, v49
	s_nop 1
	v_permlane16_swap_b32_e32 v49, v50
	v_add_f32_e32 v49, v49, v50
	v_mov_b32_e32 v50, v49
	s_nop 1
	v_permlane32_swap_b32_e32 v49, v50
	v_add_f32_e32 v49, v49, v50
	v_fmamk_f32 v49, v49, 0x3a800000, v225
	v_cmp_gt_f32_e32 vcc, s3, v49
	v_mul_f32_e32 v50, 0x4b800000, v49
	s_nop 0
	v_cndmask_b32_e32 v49, v49, v50, vcc
	v_rsq_f32_e32 v49, v49
	s_nop 0
	v_mul_f32_e32 v50, 0x45800000, v49
	v_cndmask_b32_e32 v50, v49, v50, vcc
	v_pk_mul_f32 v[44:45], v[44:45], v[50:51] op_sel_hi:[1,0]
	v_pk_mul_f32 v[40:41], v[40:41], v[50:51] op_sel_hi:[1,0]
	v_mul_f32_e32 v49, 0xbfb8aa3b, v44
	v_exp_f32_e32 v49, v49
	v_pk_mul_f32 v[42:43], v[42:43], v[50:51] op_sel_hi:[1,0]
	v_pk_mul_f32 v[36:37], v[36:37], v[50:51] op_sel_hi:[1,0]
	v_pk_mul_f32 v[32:33], v[32:33], v[50:51] op_sel_hi:[1,0]
	v_add_f32_e32 v49, 1.0, v49
	v_rcp_f32_e32 v54, v49
	v_mul_f32_e32 v49, 0xbfb8aa3b, v45
	v_exp_f32_e32 v49, v49
	v_pk_mul_f32 v[34:35], v[34:35], v[50:51] op_sel_hi:[1,0]
	v_add_f32_e32 v49, 1.0, v49
	v_rcp_f32_e32 v55, v49
	s_nop 0
	v_pk_mul_f32 v[44:45], v[44:45], v[54:55]
	s_nop 0
	v_pk_mul_f32 v[40:41], v[40:41], v[44:45]
	v_pk_mul_f32 v[44:45], v[46:47], v[50:51] op_sel_hi:[1,0]
	s_nop 0
	v_mul_f32_e32 v46, 0xbfb8aa3b, v44
	v_mul_f32_e32 v47, 0xbfb8aa3b, v45
	v_exp_f32_e32 v46, v46
	v_exp_f32_e32 v47, v47
	v_add_f32_e32 v46, 1.0, v46
	v_add_f32_e32 v47, 1.0, v47
	v_rcp_f32_e32 v46, v46
	v_rcp_f32_e32 v47, v47
	s_nop 0
	v_pk_mul_f32 v[44:45], v[44:45], v[46:47]
	s_nop 0
	v_pk_mul_f32 v[42:43], v[42:43], v[44:45]
	v_mul_f32_e32 v44, 0xbfb8aa3b, v36
	v_mul_f32_e32 v45, 0xbfb8aa3b, v37
	v_exp_f32_e32 v44, v44
	v_exp_f32_e32 v45, v45
	v_add_f32_e32 v44, 1.0, v44
	v_add_f32_e32 v45, 1.0, v45
	v_rcp_f32_e32 v44, v44
	v_rcp_f32_e32 v45, v45
	s_nop 0
	v_pk_mul_f32 v[36:37], v[36:37], v[44:45]
	s_nop 0
	v_pk_mul_f32 v[36:37], v[32:33], v[36:37]
	v_pk_mul_f32 v[32:33], v[38:39], v[50:51] op_sel_hi:[1,0]
	s_nop 0
	v_mul_f32_e32 v38, 0xbfb8aa3b, v32
	v_mul_f32_e32 v39, 0xbfb8aa3b, v33
	v_exp_f32_e32 v38, v38
	v_exp_f32_e32 v39, v39
	v_add_f32_e32 v38, 1.0, v38
	v_add_f32_e32 v39, 1.0, v39
	v_rcp_f32_e32 v38, v38
	v_rcp_f32_e32 v39, v39
	s_nop 0
	v_pk_mul_f32 v[32:33], v[32:33], v[38:39]
	s_nop 0
	v_pk_mul_f32 v[38:39], v[34:35], v[32:33]
	v_cvt_pk_bf16_f32 v34, v36, v37
	v_mad_i64_i32 v[36:37], s[4:5], v48, s16, v[52:53]
	v_lshl_add_u64 v[36:37], v[36:37], 0, s[38:39]
	v_lshl_add_u64 v[36:37], v[36:37], 0, s[68:69]
	v_cvt_pk_bf16_f32 v32, v40, v41
	v_cvt_pk_bf16_f32 v33, v42, v43
	v_cvt_pk_bf16_f32 v35, v38, v39
	v_lshl_add_u64 v[36:37], v[36:37], 0, v[96:97]
	global_store_dwordx4 v[36:37], v[32:35], off sc1
	s_nop 1
	v_add_u32_e32 v32, 0xa0, v130
	v_ashrrev_i32_e32 v33, 31, v32
	v_lshlrev_b64 v[34:35], 6, v[32:33]
	v_lshl_add_u64 v[34:35], v[204:205], 0, v[34:35]
	s_waitcnt vmcnt(7)
	v_add_f32_e32 v33, v160, v161
	v_add_f32_e32 v34, v162, v163
	v_add_f32_e32 v33, v33, v34
	v_mov_b32_e32 v34, v33
	s_nop 1
	v_permlane16_swap_b32_e32 v33, v34
	v_add_f32_e32 v33, v33, v34
	v_mov_b32_e32 v34, v33
	s_nop 1
	v_permlane32_swap_b32_e32 v33, v34
	v_add_f32_e32 v33, v33, v34
	v_fmamk_f32 v33, v33, 0x3a800000, v225
	v_cmp_gt_f32_e32 vcc, s3, v33
	v_mul_f32_e32 v34, 0x4b800000, v33
	s_nop 0
	v_cndmask_b32_e32 v33, v33, v34, vcc
	v_rsq_f32_e32 v33, v33
	s_nop 0
	v_mul_f32_e32 v34, 0x45800000, v33
	v_cndmask_b32_e32 v34, v33, v34, vcc
	v_pk_mul_f32 v[28:29], v[28:29], v[34:35] op_sel_hi:[1,0]
	v_pk_mul_f32 v[24:25], v[24:25], v[34:35] op_sel_hi:[1,0]
	v_mul_f32_e32 v33, 0xbfb8aa3b, v28
	v_exp_f32_e32 v33, v33
	v_pk_mul_f32 v[26:27], v[26:27], v[34:35] op_sel_hi:[1,0]
	v_pk_mul_f32 v[20:21], v[20:21], v[34:35] op_sel_hi:[1,0]
	v_pk_mul_f32 v[16:17], v[16:17], v[34:35] op_sel_hi:[1,0]
	v_add_f32_e32 v33, 1.0, v33
	v_rcp_f32_e32 v36, v33
	v_mul_f32_e32 v33, 0xbfb8aa3b, v29
	v_exp_f32_e32 v33, v33
	v_pk_mul_f32 v[18:19], v[18:19], v[34:35] op_sel_hi:[1,0]
	v_add_f32_e32 v33, 1.0, v33
	v_rcp_f32_e32 v37, v33
	s_nop 0
	v_pk_mul_f32 v[28:29], v[28:29], v[36:37]
	s_nop 0
	v_pk_mul_f32 v[24:25], v[24:25], v[28:29]
	v_pk_mul_f32 v[28:29], v[30:31], v[34:35] op_sel_hi:[1,0]
	s_nop 0
	v_mul_f32_e32 v30, 0xbfb8aa3b, v28
	v_mul_f32_e32 v31, 0xbfb8aa3b, v29
	v_exp_f32_e32 v30, v30
	v_exp_f32_e32 v31, v31
	v_add_f32_e32 v30, 1.0, v30
	v_add_f32_e32 v31, 1.0, v31
	v_rcp_f32_e32 v30, v30
	v_rcp_f32_e32 v31, v31
	s_nop 0
	v_pk_mul_f32 v[28:29], v[28:29], v[30:31]
	s_nop 0
	v_pk_mul_f32 v[26:27], v[26:27], v[28:29]
	v_mul_f32_e32 v28, 0xbfb8aa3b, v20
	v_mul_f32_e32 v29, 0xbfb8aa3b, v21
	v_exp_f32_e32 v28, v28
	v_exp_f32_e32 v29, v29
	v_add_f32_e32 v28, 1.0, v28
	v_add_f32_e32 v29, 1.0, v29
	v_rcp_f32_e32 v28, v28
	v_rcp_f32_e32 v29, v29
	s_nop 0
	v_pk_mul_f32 v[20:21], v[20:21], v[28:29]
	s_nop 0
	v_pk_mul_f32 v[20:21], v[16:17], v[20:21]
	v_pk_mul_f32 v[16:17], v[22:23], v[34:35] op_sel_hi:[1,0]
	s_nop 0
	v_mul_f32_e32 v22, 0xbfb8aa3b, v16
	v_mul_f32_e32 v23, 0xbfb8aa3b, v17
	v_exp_f32_e32 v22, v22
	v_exp_f32_e32 v23, v23
	v_add_f32_e32 v22, 1.0, v22
	v_add_f32_e32 v23, 1.0, v23
	v_rcp_f32_e32 v22, v22
	v_rcp_f32_e32 v23, v23
	s_nop 0
	v_pk_mul_f32 v[16:17], v[16:17], v[22:23]
	s_nop 0
	v_pk_mul_f32 v[22:23], v[18:19], v[16:17]
	v_cvt_pk_bf16_f32 v18, v20, v21
	v_mad_i64_i32 v[20:21], s[4:5], v32, s16, v[52:53]
	v_lshl_add_u64 v[20:21], v[20:21], 0, s[38:39]
	v_lshl_add_u64 v[20:21], v[20:21], 0, s[68:69]
	v_cvt_pk_bf16_f32 v16, v24, v25
	v_cvt_pk_bf16_f32 v17, v26, v27
	v_cvt_pk_bf16_f32 v19, v22, v23
	v_lshl_add_u64 v[20:21], v[20:21], 0, v[96:97]
	global_store_dwordx4 v[20:21], v[16:19], off sc1
	s_nop 1
	v_add_u32_e32 v16, 0xb0, v130
	v_ashrrev_i32_e32 v17, 31, v16
	v_lshlrev_b64 v[18:19], 6, v[16:17]
	v_lshl_add_u64 v[18:19], v[204:205], 0, v[18:19]
	s_waitcnt vmcnt(7)
	v_add_f32_e32 v17, v164, v165
	v_add_f32_e32 v18, v166, v167
	v_add_f32_e32 v17, v17, v18
	v_mov_b32_e32 v18, v17
	s_nop 1
	v_permlane16_swap_b32_e32 v17, v18
	v_add_f32_e32 v17, v17, v18
	v_mov_b32_e32 v18, v17
	s_nop 1
	v_permlane32_swap_b32_e32 v17, v18
	v_add_f32_e32 v17, v17, v18
	v_fmamk_f32 v17, v17, 0x3a800000, v225
	v_cmp_gt_f32_e32 vcc, s3, v17
	v_mul_f32_e32 v18, 0x4b800000, v17
	s_nop 0
	v_cndmask_b32_e32 v17, v17, v18, vcc
	v_rsq_f32_e32 v17, v17
	s_nop 0
	v_mul_f32_e32 v18, 0x45800000, v17
	v_cndmask_b32_e32 v18, v17, v18, vcc
	v_pk_mul_f32 v[12:13], v[12:13], v[18:19] op_sel_hi:[1,0]
	v_pk_mul_f32 v[8:9], v[8:9], v[18:19] op_sel_hi:[1,0]
	v_mul_f32_e32 v17, 0xbfb8aa3b, v12
	v_exp_f32_e32 v17, v17
	v_pk_mul_f32 v[10:11], v[10:11], v[18:19] op_sel_hi:[1,0]
	v_pk_mul_f32 v[4:5], v[4:5], v[18:19] op_sel_hi:[1,0]
	v_pk_mul_f32 v[0:1], v[0:1], v[18:19] op_sel_hi:[1,0]
	v_add_f32_e32 v17, 1.0, v17
	v_rcp_f32_e32 v20, v17
	v_mul_f32_e32 v17, 0xbfb8aa3b, v13
	v_exp_f32_e32 v17, v17
	v_pk_mul_f32 v[2:3], v[2:3], v[18:19] op_sel_hi:[1,0]
	v_add_f32_e32 v17, 1.0, v17
	v_rcp_f32_e32 v21, v17
	s_nop 0
	v_pk_mul_f32 v[12:13], v[12:13], v[20:21]
	s_nop 0
	v_pk_mul_f32 v[8:9], v[8:9], v[12:13]
	v_pk_mul_f32 v[12:13], v[14:15], v[18:19] op_sel_hi:[1,0]
	s_nop 0
	v_mul_f32_e32 v14, 0xbfb8aa3b, v12
	v_mul_f32_e32 v15, 0xbfb8aa3b, v13
	v_exp_f32_e32 v14, v14
	v_exp_f32_e32 v15, v15
	v_add_f32_e32 v14, 1.0, v14
	v_add_f32_e32 v15, 1.0, v15
	v_rcp_f32_e32 v14, v14
	v_rcp_f32_e32 v15, v15
	s_nop 0
	v_pk_mul_f32 v[12:13], v[12:13], v[14:15]
	s_nop 0
	v_pk_mul_f32 v[10:11], v[10:11], v[12:13]
	v_mul_f32_e32 v12, 0xbfb8aa3b, v4
	v_mul_f32_e32 v13, 0xbfb8aa3b, v5
	v_exp_f32_e32 v12, v12
	v_exp_f32_e32 v13, v13
	v_add_f32_e32 v12, 1.0, v12
	v_add_f32_e32 v13, 1.0, v13
	v_rcp_f32_e32 v12, v12
	v_rcp_f32_e32 v13, v13
	s_nop 0
	v_pk_mul_f32 v[4:5], v[4:5], v[12:13]
	s_nop 0
	v_pk_mul_f32 v[4:5], v[0:1], v[4:5]
	v_pk_mul_f32 v[0:1], v[6:7], v[18:19] op_sel_hi:[1,0]
	s_nop 0
	v_mul_f32_e32 v6, 0xbfb8aa3b, v0
	v_mul_f32_e32 v7, 0xbfb8aa3b, v1
	v_exp_f32_e32 v6, v6
	v_exp_f32_e32 v7, v7
	v_add_f32_e32 v6, 1.0, v6
	v_add_f32_e32 v7, 1.0, v7
	v_rcp_f32_e32 v6, v6
	v_rcp_f32_e32 v7, v7
	s_nop 0
	v_pk_mul_f32 v[0:1], v[0:1], v[6:7]
	s_nop 0
	v_pk_mul_f32 v[6:7], v[2:3], v[0:1]
	v_cvt_pk_bf16_f32 v2, v4, v5
	v_mad_i64_i32 v[4:5], s[4:5], v16, s16, v[52:53]
	v_lshl_add_u64 v[4:5], v[4:5], 0, s[38:39]
	v_lshl_add_u64 v[4:5], v[4:5], 0, s[68:69]
	v_cvt_pk_bf16_f32 v0, v8, v9
	v_cvt_pk_bf16_f32 v1, v10, v11
	v_cvt_pk_bf16_f32 v3, v6, v7
	v_lshl_add_u64 v[4:5], v[4:5], 0, v[96:97]
	global_store_dwordx4 v[4:5], v[0:3], off sc1
	s_and_b64 vcc, exec, s[36:37]
	s_mov_b64 s[30:31], -1
	s_cbranch_vccnz .LBB0_349

.LBB0_542:
	v_lshl_add_u32 v130, s68, 8, v205
	v_ashrrev_i32_e32 v131, 31, v130
	v_lshlrev_b64 v[132:133], 6, v[130:131]
	v_lshl_add_u64 v[132:133], v[206:207], 0, v[132:133]
	global_load_dwordx4 v[146:149], v[132:133], off
	global_load_dwordx4 v[150:153], v[132:133], off offset:1024
	global_load_dwordx4 v[154:157], v[132:133], off offset:2048
	global_load_dwordx4 v[158:161], v[132:133], off offset:3072
	v_add_u32_e32 v178, 0x80, v130
	v_ashrrev_i32_e32 v179, 31, v178
	v_lshlrev_b64 v[178:179], 6, v[178:179]
	v_lshl_add_u64 v[178:179], v[206:207], 0, v[178:179]
	global_load_dwordx4 v[162:165], v[178:179], off
	global_load_dwordx4 v[166:169], v[178:179], off offset:1024
	global_load_dwordx4 v[170:173], v[178:179], off offset:2048
	global_load_dwordx4 v[174:177], v[178:179], off offset:3072
	s_cmp_gt_i32 s77, 7
	s_cselect_b64 s[40:41], -1, 0
	s_lshl_b32 s30, s77, 8
	s_add_i32 s68, s30, 0xfffff800
	s_mov_b64 s[38:39], -1
	s_waitcnt vmcnt(7)
	v_add_f32_e32 v96, v146, v147
	v_add_f32_e32 v132, v148, v149
	v_add_f32_e32 v96, v96, v132
	v_mov_b32_e32 v132, v96
	s_nop 1
	v_permlane16_swap_b32_e32 v96, v132
	v_add_f32_e32 v96, v96, v132
	v_mov_b32_e32 v132, v96
	s_nop 1
	v_permlane32_swap_b32_e32 v96, v132
	v_add_f32_e32 v96, v96, v132
	v_fmamk_f32 v96, v96, 0x3a800000, v225
	v_cmp_gt_f32_e32 vcc, s3, v96
	v_mul_f32_e32 v132, 0x4b800000, v96
	v_lshlrev_b64 v[134:135], 11, v[130:131]
	v_cndmask_b32_e32 v96, v96, v132, vcc
	v_rsq_f32_e32 v96, v96
	s_nop 0
	v_mul_f32_e32 v132, 0x45800000, v96
	v_cndmask_b32_e32 v132, v96, v132, vcc
	s_and_b64 vcc, exec, s[40:41]
	v_lshlrev_b32_e32 v96, 1, v204
	s_cbranch_vccz .LBB0_544
	v_lshl_add_u64 v[136:137], s[26:27], 0, v[134:135]
	v_lshl_add_u64 v[136:137], s[68:69], 1, v[136:137]
	s_lshl_b32 s30, s62, 1
	s_mov_b32 s31, s69
	v_lshl_add_u64 v[136:137], v[136:137], 0, s[30:31]
	v_lshl_add_u64 v[140:141], v[136:137], 0, v[96:97]
	v_pk_mul_f32 v[138:139], v[128:129], v[132:133] op_sel_hi:[1,0]
	v_pk_mul_f32 v[136:137], v[126:127], v[132:133] op_sel_hi:[1,0]
	v_pk_mul_f32 v[142:143], v[120:121], v[132:133] op_sel_hi:[1,0]
	v_pk_mul_f32 v[144:145], v[118:119], v[132:133] op_sel_hi:[1,0]
	v_cvt_pk_bf16_f32 v136, v136, v137
	v_cvt_pk_bf16_f32 v137, v138, v139
	v_cvt_pk_bf16_f32 v138, v144, v145
	v_cvt_pk_bf16_f32 v139, v142, v143
	global_store_dwordx4 v[140:141], v[136:139], off sc1
	v_pk_mul_f32 v[142:143], v[116:117], v[132:133] op_sel_hi:[1,0]
	v_pk_mul_f32 v[144:145], v[114:115], v[132:133] op_sel_hi:[1,0]
	v_pk_mul_f32 v[138:139], v[124:125], v[132:133] op_sel_hi:[1,0]
	v_pk_mul_f32 v[136:137], v[122:123], v[132:133] op_sel_hi:[1,0]
	s_mov_b64 s[38:39], 0
	v_cvt_pk_bf16_f32 v136, v136, v137
	v_cvt_pk_bf16_f32 v137, v138, v139
	v_cvt_pk_bf16_f32 v138, v144, v145
	v_cvt_pk_bf16_f32 v139, v142, v143
	global_store_dwordx4 v[140:141], v[136:139], off offset:256 sc1
.LBB0_544:
	s_lshl_b32 s30, s77, 7
	s_andn2_b64 vcc, exec, s[38:39]
	s_ashr_i32 s31, s30, 31
	s_cbranch_vccnz .LBB0_546
	v_mul_f32_e32 v132, v132, v132
	v_pk_mul_f32 v[116:117], v[116:117], v[120:121]
	v_pk_mul_f32 v[114:115], v[114:115], v[118:119]
	v_pk_mul_f32 v[118:119], v[116:117], v[132:133] op_sel_hi:[1,0]
	v_pk_mul_f32 v[116:117], v[114:115], v[132:133] op_sel_hi:[1,0]
	v_pk_mul_f32 v[124:125], v[124:125], v[128:129]
	v_cvt_pk_bf16_f32 v116, v116, v117
	v_cvt_pk_bf16_f32 v117, v118, v119
	v_lshl_add_u64 v[118:119], s[24:25], 0, v[134:135]
	v_pk_mul_f32 v[122:123], v[122:123], v[126:127]
	v_lshl_add_u64 v[118:119], s[30:31], 1, v[118:119]
	s_lshl_b32 s38, s62, 1
	s_mov_b32 s39, s69
	v_pk_mul_f32 v[124:125], v[124:125], v[132:133] op_sel_hi:[1,0]
	v_pk_mul_f32 v[122:123], v[122:123], v[132:133] op_sel_hi:[1,0]
	v_lshl_add_u64 v[118:119], v[118:119], 0, s[38:39]
	v_cvt_pk_bf16_f32 v114, v122, v123
	v_cvt_pk_bf16_f32 v115, v124, v125
	v_lshl_add_u64 v[118:119], v[118:119], 0, v[96:97]
	global_store_dwordx4 v[118:119], v[114:117], off sc1
.LBB0_546:
	v_or_b32_e32 v118, 16, v130
	v_ashrrev_i32_e32 v119, 31, v118
	v_lshlrev_b64 v[114:115], 6, v[118:119]
	v_lshl_add_u64 v[114:115], v[206:207], 0, v[114:115]
	s_mov_b64 s[60:61], -1
	s_waitcnt vmcnt(7)
	v_add_f32_e32 v114, v150, v151
	v_add_f32_e32 v115, v152, v153
	v_add_f32_e32 v114, v114, v115
	v_mov_b32_e32 v115, v114
	s_nop 1
	v_permlane16_swap_b32_e32 v114, v115
	v_add_f32_e32 v114, v114, v115
	v_mov_b32_e32 v115, v114
	s_nop 1
	v_permlane32_swap_b32_e32 v114, v115
	v_add_f32_e32 v114, v114, v115
	v_fmamk_f32 v114, v114, 0x3a800000, v225
	v_cmp_gt_f32_e32 vcc, s3, v114
	v_mul_f32_e32 v115, 0x4b800000, v114
	v_lshlrev_b64 v[116:117], 11, v[118:119]
	v_cndmask_b32_e32 v114, v114, v115, vcc
	v_rsq_f32_e32 v114, v114
	s_nop 0
	v_mul_f32_e32 v115, 0x45800000, v114
	v_cndmask_b32_e32 v114, v114, v115, vcc
	v_cndmask_b32_e64 v115, 0, 1, s[40:41]
	v_cmp_ne_u32_e64 s[38:39], 1, v115
	s_andn2_b64 vcc, exec, s[40:41]
	s_cbranch_vccnz .LBB0_548
	v_lshl_add_u64 v[118:119], s[26:27], 0, v[116:117]
	v_lshl_add_u64 v[118:119], s[68:69], 1, v[118:119]
	s_lshl_b32 s40, s62, 1
	s_mov_b32 s41, s69
	v_lshl_add_u64 v[118:119], v[118:119], 0, s[40:41]
	v_lshl_add_u64 v[122:123], v[118:119], 0, v[96:97]
	v_pk_mul_f32 v[120:121], v[112:113], v[114:115] op_sel_hi:[1,0]
	v_pk_mul_f32 v[118:119], v[110:111], v[114:115] op_sel_hi:[1,0]
	v_pk_mul_f32 v[124:125], v[104:105], v[114:115] op_sel_hi:[1,0]
	v_pk_mul_f32 v[126:127], v[102:103], v[114:115] op_sel_hi:[1,0]
	v_cvt_pk_bf16_f32 v118, v118, v119
	v_cvt_pk_bf16_f32 v119, v120, v121
	v_cvt_pk_bf16_f32 v120, v126, v127
	v_cvt_pk_bf16_f32 v121, v124, v125
	global_store_dwordx4 v[122:123], v[118:121], off sc1
	v_pk_mul_f32 v[124:125], v[100:101], v[114:115] op_sel_hi:[1,0]
	v_pk_mul_f32 v[126:127], v[98:99], v[114:115] op_sel_hi:[1,0]
	v_pk_mul_f32 v[120:121], v[108:109], v[114:115] op_sel_hi:[1,0]
	v_pk_mul_f32 v[118:119], v[106:107], v[114:115] op_sel_hi:[1,0]
	s_mov_b64 s[60:61], 0
	v_cvt_pk_bf16_f32 v118, v118, v119
	v_cvt_pk_bf16_f32 v119, v120, v121
	v_cvt_pk_bf16_f32 v120, v126, v127
	v_cvt_pk_bf16_f32 v121, v124, v125
	global_store_dwordx4 v[122:123], v[118:121], off offset:256 sc1
.LBB0_548:
	s_andn2_b64 vcc, exec, s[60:61]
	s_cbranch_vccnz .LBB0_550
	v_mul_f32_e32 v114, v114, v114
	v_pk_mul_f32 v[100:101], v[100:101], v[104:105]
	v_pk_mul_f32 v[98:99], v[98:99], v[102:103]
	v_pk_mul_f32 v[102:103], v[100:101], v[114:115] op_sel_hi:[1,0]
	v_pk_mul_f32 v[100:101], v[98:99], v[114:115] op_sel_hi:[1,0]
	v_pk_mul_f32 v[108:109], v[108:109], v[112:113]
	v_cvt_pk_bf16_f32 v100, v100, v101
	v_cvt_pk_bf16_f32 v101, v102, v103
	v_lshl_add_u64 v[102:103], s[24:25], 0, v[116:117]
	v_pk_mul_f32 v[106:107], v[106:107], v[110:111]
	v_lshl_add_u64 v[102:103], s[30:31], 1, v[102:103]
	s_lshl_b32 s40, s62, 1
	s_mov_b32 s41, s69
	v_pk_mul_f32 v[108:109], v[108:109], v[114:115] op_sel_hi:[1,0]
	v_pk_mul_f32 v[106:107], v[106:107], v[114:115] op_sel_hi:[1,0]
	v_lshl_add_u64 v[102:103], v[102:103], 0, s[40:41]
	v_cvt_pk_bf16_f32 v98, v106, v107
	v_cvt_pk_bf16_f32 v99, v108, v109
	v_lshl_add_u64 v[102:103], v[102:103], 0, v[96:97]
	global_store_dwordx4 v[102:103], v[98:101], off sc1
.LBB0_550:
	v_or_b32_e32 v102, 32, v130
	v_ashrrev_i32_e32 v103, 31, v102
	v_lshlrev_b64 v[98:99], 6, v[102:103]
	v_lshl_add_u64 v[98:99], v[206:207], 0, v[98:99]
	s_mov_b64 s[40:41], -1
	s_waitcnt vmcnt(7)
	v_add_f32_e32 v98, v154, v155
	v_add_f32_e32 v99, v156, v157
	v_add_f32_e32 v98, v98, v99
	v_mov_b32_e32 v99, v98
	s_nop 1
	v_permlane16_swap_b32_e32 v98, v99
	v_add_f32_e32 v98, v98, v99
	v_mov_b32_e32 v99, v98
	s_nop 1
	v_permlane32_swap_b32_e32 v98, v99
	v_add_f32_e32 v98, v98, v99
	v_fmamk_f32 v98, v98, 0x3a800000, v225
	v_cmp_gt_f32_e32 vcc, s3, v98
	v_mul_f32_e32 v99, 0x4b800000, v98
	s_nop 0
	v_cndmask_b32_e32 v98, v98, v99, vcc
	v_rsq_f32_e32 v98, v98
	s_nop 0
	v_mul_f32_e32 v99, 0x45800000, v98
	v_cndmask_b32_e32 v100, v98, v99, vcc
	s_and_b64 vcc, exec, s[38:39]
	v_lshlrev_b64 v[98:99], 11, v[102:103]
	s_cbranch_vccnz .LBB0_552
	v_lshl_add_u64 v[102:103], s[26:27], 0, v[98:99]
	v_lshl_add_u64 v[102:103], s[68:69], 1, v[102:103]
	s_lshl_b32 s40, s62, 1
	s_mov_b32 s41, s69
	v_lshl_add_u64 v[102:103], v[102:103], 0, s[40:41]
	v_lshl_add_u64 v[106:107], v[102:103], 0, v[96:97]
	v_pk_mul_f32 v[104:105], v[94:95], v[100:101] op_sel_hi:[1,0]
	v_pk_mul_f32 v[102:103], v[92:93], v[100:101] op_sel_hi:[1,0]
	v_pk_mul_f32 v[108:109], v[86:87], v[100:101] op_sel_hi:[1,0]
	v_pk_mul_f32 v[110:111], v[84:85], v[100:101] op_sel_hi:[1,0]
	v_cvt_pk_bf16_f32 v102, v102, v103
	v_cvt_pk_bf16_f32 v103, v104, v105
	v_cvt_pk_bf16_f32 v104, v110, v111
	v_cvt_pk_bf16_f32 v105, v108, v109
	global_store_dwordx4 v[106:107], v[102:105], off sc1
	v_pk_mul_f32 v[108:109], v[82:83], v[100:101] op_sel_hi:[1,0]
	v_pk_mul_f32 v[110:111], v[80:81], v[100:101] op_sel_hi:[1,0]
	v_pk_mul_f32 v[104:105], v[90:91], v[100:101] op_sel_hi:[1,0]
	v_pk_mul_f32 v[102:103], v[88:89], v[100:101] op_sel_hi:[1,0]
	s_mov_b64 s[40:41], 0
	v_cvt_pk_bf16_f32 v102, v102, v103
	v_cvt_pk_bf16_f32 v103, v104, v105
	v_cvt_pk_bf16_f32 v104, v110, v111
	v_cvt_pk_bf16_f32 v105, v108, v109
	global_store_dwordx4 v[106:107], v[102:105], off offset:256 sc1
.LBB0_552:
	s_andn2_b64 vcc, exec, s[40:41]
	s_cbranch_vccnz .LBB0_554
	v_mul_f32_e32 v100, v100, v100
	v_pk_mul_f32 v[82:83], v[82:83], v[86:87]
	v_pk_mul_f32 v[80:81], v[80:81], v[84:85]
	v_pk_mul_f32 v[84:85], v[82:83], v[100:101] op_sel_hi:[1,0]
	v_pk_mul_f32 v[82:83], v[80:81], v[100:101] op_sel_hi:[1,0]
	v_pk_mul_f32 v[90:91], v[90:91], v[94:95]
	v_cvt_pk_bf16_f32 v82, v82, v83
	v_cvt_pk_bf16_f32 v83, v84, v85
	v_lshl_add_u64 v[84:85], s[24:25], 0, v[98:99]
	v_pk_mul_f32 v[88:89], v[88:89], v[92:93]
	v_lshl_add_u64 v[84:85], s[30:31], 1, v[84:85]
	s_lshl_b32 s40, s62, 1
	s_mov_b32 s41, s69
	v_pk_mul_f32 v[90:91], v[90:91], v[100:101] op_sel_hi:[1,0]
	v_pk_mul_f32 v[88:89], v[88:89], v[100:101] op_sel_hi:[1,0]
	v_lshl_add_u64 v[84:85], v[84:85], 0, s[40:41]
	v_cvt_pk_bf16_f32 v80, v88, v89
	v_cvt_pk_bf16_f32 v81, v90, v91
	v_lshl_add_u64 v[84:85], v[84:85], 0, v[96:97]
	global_store_dwordx4 v[84:85], v[80:83], off sc1
.LBB0_554:
	v_or_b32_e32 v84, 48, v130
	v_ashrrev_i32_e32 v85, 31, v84
	v_lshlrev_b64 v[80:81], 6, v[84:85]
	v_lshl_add_u64 v[80:81], v[206:207], 0, v[80:81]
	s_mov_b64 s[40:41], -1
	s_waitcnt vmcnt(7)
	v_add_f32_e32 v80, v158, v159
	v_add_f32_e32 v81, v160, v161
	v_add_f32_e32 v80, v80, v81
	v_mov_b32_e32 v81, v80
	s_nop 1
	v_permlane16_swap_b32_e32 v80, v81
	v_add_f32_e32 v80, v80, v81
	v_mov_b32_e32 v81, v80
	s_nop 1
	v_permlane32_swap_b32_e32 v80, v81
	v_add_f32_e32 v80, v80, v81
	v_fmamk_f32 v80, v80, 0x3a800000, v225
	v_cmp_gt_f32_e32 vcc, s3, v80
	v_mul_f32_e32 v81, 0x4b800000, v80
	s_nop 0
	v_cndmask_b32_e32 v80, v80, v81, vcc
	v_rsq_f32_e32 v80, v80
	s_nop 0
	v_mul_f32_e32 v81, 0x45800000, v80
	v_cndmask_b32_e32 v82, v80, v81, vcc
	s_and_b64 vcc, exec, s[38:39]
	v_lshlrev_b64 v[80:81], 11, v[84:85]
	s_cbranch_vccnz .LBB0_556
	v_lshl_add_u64 v[84:85], s[26:27], 0, v[80:81]
	v_lshl_add_u64 v[84:85], s[68:69], 1, v[84:85]
	s_lshl_b32 s40, s62, 1
	s_mov_b32 s41, s69
	v_lshl_add_u64 v[84:85], v[84:85], 0, s[40:41]
	v_lshl_add_u64 v[88:89], v[84:85], 0, v[96:97]
	v_pk_mul_f32 v[86:87], v[78:79], v[82:83] op_sel_hi:[1,0]
	v_pk_mul_f32 v[84:85], v[76:77], v[82:83] op_sel_hi:[1,0]
	v_pk_mul_f32 v[90:91], v[70:71], v[82:83] op_sel_hi:[1,0]
	v_pk_mul_f32 v[92:93], v[68:69], v[82:83] op_sel_hi:[1,0]
	v_cvt_pk_bf16_f32 v84, v84, v85
	v_cvt_pk_bf16_f32 v85, v86, v87
	v_cvt_pk_bf16_f32 v86, v92, v93
	v_cvt_pk_bf16_f32 v87, v90, v91
	global_store_dwordx4 v[88:89], v[84:87], off sc1
	v_pk_mul_f32 v[90:91], v[66:67], v[82:83] op_sel_hi:[1,0]
	v_pk_mul_f32 v[92:93], v[64:65], v[82:83] op_sel_hi:[1,0]
	v_pk_mul_f32 v[86:87], v[74:75], v[82:83] op_sel_hi:[1,0]
	v_pk_mul_f32 v[84:85], v[72:73], v[82:83] op_sel_hi:[1,0]
	s_mov_b64 s[40:41], 0
	v_cvt_pk_bf16_f32 v84, v84, v85
	v_cvt_pk_bf16_f32 v85, v86, v87
	v_cvt_pk_bf16_f32 v86, v92, v93
	v_cvt_pk_bf16_f32 v87, v90, v91
	global_store_dwordx4 v[88:89], v[84:87], off offset:256 sc1
.LBB0_556:
	s_andn2_b64 vcc, exec, s[40:41]
	s_cbranch_vccnz .LBB0_558
	v_mul_f32_e32 v82, v82, v82
	v_pk_mul_f32 v[66:67], v[66:67], v[70:71]
	v_pk_mul_f32 v[64:65], v[64:65], v[68:69]
	v_pk_mul_f32 v[68:69], v[66:67], v[82:83] op_sel_hi:[1,0]
	v_pk_mul_f32 v[66:67], v[64:65], v[82:83] op_sel_hi:[1,0]
	v_pk_mul_f32 v[74:75], v[74:75], v[78:79]
	v_cvt_pk_bf16_f32 v66, v66, v67
	v_cvt_pk_bf16_f32 v67, v68, v69
	v_lshl_add_u64 v[68:69], s[24:25], 0, v[80:81]
	v_pk_mul_f32 v[72:73], v[72:73], v[76:77]
	v_lshl_add_u64 v[68:69], s[30:31], 1, v[68:69]
	s_lshl_b32 s40, s62, 1
	s_mov_b32 s41, s69
	v_pk_mul_f32 v[74:75], v[74:75], v[82:83] op_sel_hi:[1,0]
	v_pk_mul_f32 v[72:73], v[72:73], v[82:83] op_sel_hi:[1,0]
	v_lshl_add_u64 v[68:69], v[68:69], 0, s[40:41]
	v_cvt_pk_bf16_f32 v64, v72, v73
	v_cvt_pk_bf16_f32 v65, v74, v75
	v_lshl_add_u64 v[68:69], v[68:69], 0, v[96:97]
	global_store_dwordx4 v[68:69], v[64:67], off sc1
.LBB0_558:
	v_add_u32_e32 v68, 0x80, v130
	v_ashrrev_i32_e32 v69, 31, v68
	v_lshlrev_b64 v[64:65], 6, v[68:69]
	v_lshl_add_u64 v[64:65], v[206:207], 0, v[64:65]
	s_mov_b64 s[40:41], -1
	s_waitcnt vmcnt(7)
	v_add_f32_e32 v64, v162, v163
	v_add_f32_e32 v65, v164, v165
	v_add_f32_e32 v64, v64, v65
	v_mov_b32_e32 v65, v64
	s_nop 1
	v_permlane16_swap_b32_e32 v64, v65
	v_add_f32_e32 v64, v64, v65
	v_mov_b32_e32 v65, v64
	s_nop 1
	v_permlane32_swap_b32_e32 v64, v65
	v_add_f32_e32 v64, v64, v65
	v_fmamk_f32 v64, v64, 0x3a800000, v225
	v_cmp_gt_f32_e32 vcc, s3, v64
	v_mul_f32_e32 v65, 0x4b800000, v64
	s_nop 0
	v_cndmask_b32_e32 v64, v64, v65, vcc
	v_rsq_f32_e32 v64, v64
	s_nop 0
	v_mul_f32_e32 v65, 0x45800000, v64
	v_cndmask_b32_e32 v66, v64, v65, vcc
	s_and_b64 vcc, exec, s[38:39]
	v_lshlrev_b64 v[64:65], 11, v[68:69]
	s_cbranch_vccnz .LBB0_560
	v_lshl_add_u64 v[68:69], s[26:27], 0, v[64:65]
	v_lshl_add_u64 v[68:69], s[68:69], 1, v[68:69]
	s_lshl_b32 s40, s62, 1
	s_mov_b32 s41, s69
	v_lshl_add_u64 v[68:69], v[68:69], 0, s[40:41]
	v_lshl_add_u64 v[72:73], v[68:69], 0, v[96:97]
	v_pk_mul_f32 v[70:71], v[50:51], v[66:67] op_sel_hi:[1,0]
	v_pk_mul_f32 v[68:69], v[48:49], v[66:67] op_sel_hi:[1,0]
	v_pk_mul_f32 v[74:75], v[58:59], v[66:67] op_sel_hi:[1,0]
	v_pk_mul_f32 v[76:77], v[56:57], v[66:67] op_sel_hi:[1,0]
	v_cvt_pk_bf16_f32 v68, v68, v69
	v_cvt_pk_bf16_f32 v69, v70, v71
	v_cvt_pk_bf16_f32 v70, v76, v77
	v_cvt_pk_bf16_f32 v71, v74, v75
	global_store_dwordx4 v[72:73], v[68:71], off sc1
	v_pk_mul_f32 v[74:75], v[54:55], v[66:67] op_sel_hi:[1,0]
	v_pk_mul_f32 v[76:77], v[52:53], v[66:67] op_sel_hi:[1,0]
	v_pk_mul_f32 v[70:71], v[62:63], v[66:67] op_sel_hi:[1,0]
	v_pk_mul_f32 v[68:69], v[60:61], v[66:67] op_sel_hi:[1,0]
	s_mov_b64 s[40:41], 0
	v_cvt_pk_bf16_f32 v68, v68, v69
	v_cvt_pk_bf16_f32 v69, v70, v71
	v_cvt_pk_bf16_f32 v70, v76, v77
	v_cvt_pk_bf16_f32 v71, v74, v75
	global_store_dwordx4 v[72:73], v[68:71], off offset:256 sc1
.LBB0_560:
	s_andn2_b64 vcc, exec, s[40:41]
	s_cbranch_vccnz .LBB0_562
	v_mul_f32_e32 v66, v66, v66
	v_pk_mul_f32 v[50:51], v[62:63], v[50:51]
	v_pk_mul_f32 v[48:49], v[60:61], v[48:49]
	v_pk_mul_f32 v[52:53], v[52:53], v[56:57]
	v_pk_mul_f32 v[50:51], v[50:51], v[66:67] op_sel_hi:[1,0]
	v_pk_mul_f32 v[48:49], v[48:49], v[66:67] op_sel_hi:[1,0]
	v_pk_mul_f32 v[52:53], v[52:53], v[66:67] op_sel_hi:[1,0]
	v_cvt_pk_bf16_f32 v48, v48, v49
	v_cvt_pk_bf16_f32 v49, v50, v51
	v_cvt_pk_bf16_f32 v50, v52, v53
	v_lshl_add_u64 v[52:53], s[24:25], 0, v[64:65]
	v_pk_mul_f32 v[54:55], v[54:55], v[58:59]
	v_lshl_add_u64 v[52:53], s[30:31], 1, v[52:53]
	s_lshl_b32 s40, s62, 1
	s_mov_b32 s41, s69
	v_pk_mul_f32 v[54:55], v[54:55], v[66:67] op_sel_hi:[1,0]
	v_lshl_add_u64 v[52:53], v[52:53], 0, s[40:41]
	v_cvt_pk_bf16_f32 v51, v54, v55
	v_lshl_add_u64 v[52:53], v[52:53], 0, v[96:97]
	global_store_dwordx4 v[52:53], v[48:51], off sc1
.LBB0_562:
	v_add_u32_e32 v52, 0x90, v130
	v_ashrrev_i32_e32 v53, 31, v52
	v_lshlrev_b64 v[48:49], 6, v[52:53]
	v_lshl_add_u64 v[48:49], v[206:207], 0, v[48:49]
	s_mov_b64 s[40:41], -1
	s_waitcnt vmcnt(7)
	v_add_f32_e32 v48, v166, v167
	v_add_f32_e32 v49, v168, v169
	v_add_f32_e32 v48, v48, v49
	v_mov_b32_e32 v49, v48
	s_nop 1
	v_permlane16_swap_b32_e32 v48, v49
	v_add_f32_e32 v48, v48, v49
	v_mov_b32_e32 v49, v48
	s_nop 1
	v_permlane32_swap_b32_e32 v48, v49
	v_add_f32_e32 v48, v48, v49
	v_fmamk_f32 v48, v48, 0x3a800000, v225
	v_cmp_gt_f32_e32 vcc, s3, v48
	v_mul_f32_e32 v49, 0x4b800000, v48
	s_nop 0
	v_cndmask_b32_e32 v48, v48, v49, vcc
	v_rsq_f32_e32 v48, v48
	s_nop 0
	v_mul_f32_e32 v49, 0x45800000, v48
	v_cndmask_b32_e32 v50, v48, v49, vcc
	s_and_b64 vcc, exec, s[38:39]
	v_lshlrev_b64 v[48:49], 11, v[52:53]
	s_cbranch_vccnz .LBB0_564
	v_lshl_add_u64 v[52:53], s[26:27], 0, v[48:49]
	v_lshl_add_u64 v[52:53], s[68:69], 1, v[52:53]
	s_lshl_b32 s40, s62, 1
	s_mov_b32 s41, s69
	v_lshl_add_u64 v[52:53], v[52:53], 0, s[40:41]
	v_lshl_add_u64 v[56:57], v[52:53], 0, v[96:97]
	v_pk_mul_f32 v[54:55], v[46:47], v[50:51] op_sel_hi:[1,0]
	v_pk_mul_f32 v[52:53], v[44:45], v[50:51] op_sel_hi:[1,0]
	v_pk_mul_f32 v[58:59], v[38:39], v[50:51] op_sel_hi:[1,0]
	v_pk_mul_f32 v[60:61], v[36:37], v[50:51] op_sel_hi:[1,0]
	v_cvt_pk_bf16_f32 v52, v52, v53
	v_cvt_pk_bf16_f32 v53, v54, v55
	v_cvt_pk_bf16_f32 v54, v60, v61
	v_cvt_pk_bf16_f32 v55, v58, v59
	global_store_dwordx4 v[56:57], v[52:55], off sc1
	v_pk_mul_f32 v[58:59], v[34:35], v[50:51] op_sel_hi:[1,0]
	v_pk_mul_f32 v[60:61], v[32:33], v[50:51] op_sel_hi:[1,0]
	v_pk_mul_f32 v[54:55], v[42:43], v[50:51] op_sel_hi:[1,0]
	v_pk_mul_f32 v[52:53], v[40:41], v[50:51] op_sel_hi:[1,0]
	s_mov_b64 s[40:41], 0
	v_cvt_pk_bf16_f32 v52, v52, v53
	v_cvt_pk_bf16_f32 v53, v54, v55
	v_cvt_pk_bf16_f32 v54, v60, v61
	v_cvt_pk_bf16_f32 v55, v58, v59
	global_store_dwordx4 v[56:57], v[52:55], off offset:256 sc1
.LBB0_564:
	s_andn2_b64 vcc, exec, s[40:41]
	s_cbranch_vccnz .LBB0_566
	v_mul_f32_e32 v50, v50, v50
	v_pk_mul_f32 v[34:35], v[34:35], v[38:39]
	v_pk_mul_f32 v[32:33], v[32:33], v[36:37]
	v_pk_mul_f32 v[36:37], v[34:35], v[50:51] op_sel_hi:[1,0]
	v_pk_mul_f32 v[34:35], v[32:33], v[50:51] op_sel_hi:[1,0]
	v_pk_mul_f32 v[42:43], v[42:43], v[46:47]
	v_cvt_pk_bf16_f32 v34, v34, v35
	v_cvt_pk_bf16_f32 v35, v36, v37
	v_lshl_add_u64 v[36:37], s[24:25], 0, v[48:49]
	v_pk_mul_f32 v[40:41], v[40:41], v[44:45]
	v_lshl_add_u64 v[36:37], s[30:31], 1, v[36:37]
	s_lshl_b32 s40, s62, 1
	s_mov_b32 s41, s69
	v_pk_mul_f32 v[42:43], v[42:43], v[50:51] op_sel_hi:[1,0]
	v_pk_mul_f32 v[40:41], v[40:41], v[50:51] op_sel_hi:[1,0]
	v_lshl_add_u64 v[36:37], v[36:37], 0, s[40:41]
	v_cvt_pk_bf16_f32 v32, v40, v41
	v_cvt_pk_bf16_f32 v33, v42, v43
	v_lshl_add_u64 v[36:37], v[36:37], 0, v[96:97]
	global_store_dwordx4 v[36:37], v[32:35], off sc1
.LBB0_566:
	v_add_u32_e32 v36, 0xa0, v130
	v_ashrrev_i32_e32 v37, 31, v36
	v_lshlrev_b64 v[32:33], 6, v[36:37]
	v_lshl_add_u64 v[32:33], v[206:207], 0, v[32:33]
	s_mov_b64 s[40:41], -1
	s_waitcnt vmcnt(7)
	v_add_f32_e32 v32, v170, v171
	v_add_f32_e32 v33, v172, v173
	v_add_f32_e32 v32, v32, v33
	v_mov_b32_e32 v33, v32
	s_nop 1
	v_permlane16_swap_b32_e32 v32, v33
	v_add_f32_e32 v32, v32, v33
	v_mov_b32_e32 v33, v32
	s_nop 1
	v_permlane32_swap_b32_e32 v32, v33
	v_add_f32_e32 v32, v32, v33
	v_fmamk_f32 v32, v32, 0x3a800000, v225
	v_cmp_gt_f32_e32 vcc, s3, v32
	v_mul_f32_e32 v33, 0x4b800000, v32
	s_nop 0
	v_cndmask_b32_e32 v32, v32, v33, vcc
	v_rsq_f32_e32 v32, v32
	s_nop 0
	v_mul_f32_e32 v33, 0x45800000, v32
	v_cndmask_b32_e32 v34, v32, v33, vcc
	s_and_b64 vcc, exec, s[38:39]
	v_lshlrev_b64 v[32:33], 11, v[36:37]
	s_cbranch_vccnz .LBB0_568
	v_lshl_add_u64 v[36:37], s[26:27], 0, v[32:33]
	v_lshl_add_u64 v[36:37], s[68:69], 1, v[36:37]
	s_lshl_b32 s40, s62, 1
	s_mov_b32 s41, s69
	v_lshl_add_u64 v[36:37], v[36:37], 0, s[40:41]
	v_lshl_add_u64 v[40:41], v[36:37], 0, v[96:97]
	v_pk_mul_f32 v[38:39], v[30:31], v[34:35] op_sel_hi:[1,0]
	v_pk_mul_f32 v[36:37], v[28:29], v[34:35] op_sel_hi:[1,0]
	v_pk_mul_f32 v[42:43], v[22:23], v[34:35] op_sel_hi:[1,0]
	v_pk_mul_f32 v[44:45], v[20:21], v[34:35] op_sel_hi:[1,0]
	v_cvt_pk_bf16_f32 v36, v36, v37
	v_cvt_pk_bf16_f32 v37, v38, v39
	v_cvt_pk_bf16_f32 v38, v44, v45
	v_cvt_pk_bf16_f32 v39, v42, v43
	global_store_dwordx4 v[40:41], v[36:39], off sc1
	v_pk_mul_f32 v[42:43], v[18:19], v[34:35] op_sel_hi:[1,0]
	v_pk_mul_f32 v[44:45], v[16:17], v[34:35] op_sel_hi:[1,0]
	v_pk_mul_f32 v[38:39], v[26:27], v[34:35] op_sel_hi:[1,0]
	v_pk_mul_f32 v[36:37], v[24:25], v[34:35] op_sel_hi:[1,0]
	s_mov_b64 s[40:41], 0
	v_cvt_pk_bf16_f32 v36, v36, v37
	v_cvt_pk_bf16_f32 v37, v38, v39
	v_cvt_pk_bf16_f32 v38, v44, v45
	v_cvt_pk_bf16_f32 v39, v42, v43
	global_store_dwordx4 v[40:41], v[36:39], off offset:256 sc1
.LBB0_568:
	s_andn2_b64 vcc, exec, s[40:41]
	s_cbranch_vccnz .LBB0_570
	v_mul_f32_e32 v34, v34, v34
	v_pk_mul_f32 v[18:19], v[18:19], v[22:23]
	v_pk_mul_f32 v[16:17], v[16:17], v[20:21]
	v_pk_mul_f32 v[20:21], v[18:19], v[34:35] op_sel_hi:[1,0]
	v_pk_mul_f32 v[18:19], v[16:17], v[34:35] op_sel_hi:[1,0]
	v_pk_mul_f32 v[26:27], v[26:27], v[30:31]
	v_cvt_pk_bf16_f32 v18, v18, v19
	v_cvt_pk_bf16_f32 v19, v20, v21
	v_lshl_add_u64 v[20:21], s[24:25], 0, v[32:33]
	v_pk_mul_f32 v[24:25], v[24:25], v[28:29]
	v_lshl_add_u64 v[20:21], s[30:31], 1, v[20:21]
	s_lshl_b32 s40, s62, 1
	s_mov_b32 s41, s69
	v_pk_mul_f32 v[26:27], v[26:27], v[34:35] op_sel_hi:[1,0]
	v_pk_mul_f32 v[24:25], v[24:25], v[34:35] op_sel_hi:[1,0]
	v_lshl_add_u64 v[20:21], v[20:21], 0, s[40:41]
	v_cvt_pk_bf16_f32 v16, v24, v25
	v_cvt_pk_bf16_f32 v17, v26, v27
	v_lshl_add_u64 v[20:21], v[20:21], 0, v[96:97]
	global_store_dwordx4 v[20:21], v[16:19], off sc1

.LBB0_573:
	v_lshl_add_u64 v[20:21], s[26:27], 0, v[16:17]
	v_lshl_add_u64 v[20:21], s[68:69], 1, v[20:21]
	s_lshl_b32 s68, s62, 1
	v_lshl_add_u64 v[20:21], v[20:21], 0, s[68:69]
	v_lshl_add_u64 v[24:25], v[20:21], 0, v[96:97]
	v_pk_mul_f32 v[22:23], v[14:15], v[18:19] op_sel_hi:[1,0]
	v_pk_mul_f32 v[20:21], v[12:13], v[18:19] op_sel_hi:[1,0]
	v_pk_mul_f32 v[26:27], v[6:7], v[18:19] op_sel_hi:[1,0]
	v_pk_mul_f32 v[28:29], v[4:5], v[18:19] op_sel_hi:[1,0]
	v_cvt_pk_bf16_f32 v20, v20, v21
	v_cvt_pk_bf16_f32 v21, v22, v23
	v_cvt_pk_bf16_f32 v22, v28, v29
	v_cvt_pk_bf16_f32 v23, v26, v27
	global_store_dwordx4 v[24:25], v[20:23], off sc1
	v_pk_mul_f32 v[26:27], v[2:3], v[18:19] op_sel_hi:[1,0]
	v_pk_mul_f32 v[28:29], v[0:1], v[18:19] op_sel_hi:[1,0]
	v_pk_mul_f32 v[22:23], v[10:11], v[18:19] op_sel_hi:[1,0]
	v_pk_mul_f32 v[20:21], v[8:9], v[18:19] op_sel_hi:[1,0]
	s_nop 0
	v_cvt_pk_bf16_f32 v20, v20, v21
	v_cvt_pk_bf16_f32 v21, v22, v23
	v_cvt_pk_bf16_f32 v22, v28, v29
	v_cvt_pk_bf16_f32 v23, v26, v27
	global_store_dwordx4 v[24:25], v[20:23], off offset:256 sc1
	s_cbranch_execnz .LBB0_572
.LBB0_574:
	v_mul_f32_e32 v18, v18, v18
	v_pk_mul_f32 v[2:3], v[2:3], v[6:7]
	v_pk_mul_f32 v[0:1], v[0:1], v[4:5]
	v_pk_mul_f32 v[4:5], v[2:3], v[18:19] op_sel_hi:[1,0]
	v_pk_mul_f32 v[2:3], v[0:1], v[18:19] op_sel_hi:[1,0]
	v_pk_mul_f32 v[10:11], v[10:11], v[14:15]
	v_cvt_pk_bf16_f32 v2, v2, v3
	v_cvt_pk_bf16_f32 v3, v4, v5
	v_lshl_add_u64 v[4:5], s[24:25], 0, v[16:17]
	v_pk_mul_f32 v[8:9], v[8:9], v[12:13]
	v_lshl_add_u64 v[4:5], s[30:31], 1, v[4:5]
	s_lshl_b32 s68, s62, 1
	v_pk_mul_f32 v[10:11], v[10:11], v[18:19] op_sel_hi:[1,0]
	v_pk_mul_f32 v[8:9], v[8:9], v[18:19] op_sel_hi:[1,0]
	v_lshl_add_u64 v[4:5], v[4:5], 0, s[68:69]
	v_cvt_pk_bf16_f32 v0, v8, v9
	v_cvt_pk_bf16_f32 v1, v10, v11
	v_lshl_add_u64 v[4:5], v[4:5], 0, v[96:97]
	global_store_dwordx4 v[4:5], v[0:3], off sc1
	s_and_b64 vcc, exec, s[36:37]
	s_mov_b64 s[30:31], -1
	s_cbranch_vccnz .LBB0_511
